# GEMM main loops: two of the second segment's six LDS-DMA loads issued one segment later (2/4/4/6 instead of 2/6/2/6 per load segment), second-segment wait vmcnt(6)
# speedup vs baseline: 1.0098x; 1.0098x over previous
.LBB0_630:
	s_ashr_i32 s85, s84, 31
	s_lshl_b64 s[22:23], s[84:85], 20
	s_cmp_eq_u32 s52, 0
	v_mov_b64_e32 v[0:1], 0x3a0
	s_cselect_b32 s31, s14, s50
	v_cmp_lt_i64_e32 vcc, s[76:77], v[0:1]
	s_cselect_b32 s30, s15, s51
	s_cselect_b32 s38, s8, s14
	s_cselect_b32 s39, s9, s15
	s_add_u32 s76, s31, s22
	s_addc_u32 s77, s30, s23
	s_and_b64 s[22:23], vcc, exec
	s_cselect_b32 s30, s77, s89
	s_cselect_b32 s31, s76, s88
	s_ashr_i32 s83, s82, 31
	s_lshl_b64 s[22:23], s[82:83], 20
	s_add_u32 s86, s38, s22
	s_addc_u32 s87, s39, s23
	s_and_b64 s[22:23], vcc, exec
	s_cselect_b32 s38, s87, s91
	s_cselect_b32 s39, s86, s90
	s_add_u32 s88, s88, 0x80080
	s_addc_u32 s89, s89, 0
	s_add_u32 s41, s90, 0x100
	s_addc_u32 s42, s91, 0
	s_mov_b32 s43, -2
	s_add_u32 s22, s88, 0xfff80080
	s_addc_u32 s23, s89, -1
	s_add_i32 s44, 0, 0x10000
	s_cmp_eq_u32 s43, 28
	s_cselect_b32 s23, s30, s23
	s_cselect_b32 s22, s31, s22
	s_cselect_b32 s91, s38, s42
	s_cselect_b32 s90, s39, s41
	s_add_i32 s81, 0, 0x14000
	ds_read_b128 v[144:147], v222
	ds_read_b128 v[148:151], v222 offset:1024
	ds_read_b128 v[152:155], v222 offset:2048
	ds_read_b128 v[156:159], v222 offset:3072
	ds_read_b128 v[160:163], v223
	ds_read_b128 v[164:167], v223 offset:1024
	ds_read_b128 v[168:171], v223 offset:2048
	ds_read_b128 v[172:175], v223 offset:3072
	s_add_i32 m0, s57, 0xc000
	ds_read_b128 v[176:179], v143
	ds_read_b128 v[180:183], v143 offset:1024
	ds_read_b128 v[184:187], v143 offset:2048
	ds_read_b128 v[188:191], v143 offset:3072
	ds_read_b128 v[192:195], v143 offset:4096
	ds_read_b128 v[196:199], v143 offset:5120
	ds_read_b128 v[200:203], v143 offset:6144
	ds_read_b128 v[204:207], v143 offset:7168
	global_load_lds_dwordx4 v136, s[88:89]
	s_add_i32 m0, s57, 0xe000
	s_nop 0
	global_load_lds_dwordx4 v138, s[88:89]
	s_waitcnt vmcnt(8)
	s_waitcnt lgkmcnt(0)
	s_barrier
	v_mfma_f32_16x16x32_bf16 v[124:127], v[144:147], v[176:179], 0
	v_mfma_f32_16x16x32_bf16 v[120:123], v[152:155], v[176:179], 0
	v_mfma_f32_16x16x32_bf16 v[116:119], v[144:147], v[184:187], 0
	v_mfma_f32_16x16x32_bf16 v[112:115], v[152:155], v[184:187], 0
	v_mfma_f32_16x16x32_bf16 v[100:103], v[144:147], v[192:195], 0
	v_mfma_f32_16x16x32_bf16 v[96:99], v[152:155], v[192:195], 0
	v_mfma_f32_16x16x32_bf16 v[84:87], v[144:147], v[200:203], 0
	v_mfma_f32_16x16x32_bf16 v[80:83], v[152:155], v[200:203], 0
	v_mfma_f32_16x16x32_bf16 v[124:127], v[148:151], v[180:183], v[124:127]
	v_mfma_f32_16x16x32_bf16 v[120:123], v[156:159], v[180:183], v[120:123]
	v_mfma_f32_16x16x32_bf16 v[116:119], v[148:151], v[188:191], v[116:119]
	v_mfma_f32_16x16x32_bf16 v[112:115], v[156:159], v[188:191], v[112:115]
	v_mfma_f32_16x16x32_bf16 v[100:103], v[148:151], v[196:199], v[100:103]
	v_mfma_f32_16x16x32_bf16 v[96:99], v[156:159], v[196:199], v[96:99]
	v_mfma_f32_16x16x32_bf16 v[84:87], v[148:151], v[204:207], v[84:87]
	v_mfma_f32_16x16x32_bf16 v[80:83], v[156:159], v[204:207], v[80:83]
	v_mfma_f32_16x16x32_bf16 v[108:111], v[160:163], v[176:179], 0
	v_mfma_f32_16x16x32_bf16 v[104:107], v[168:171], v[176:179], 0
	v_mfma_f32_16x16x32_bf16 v[92:95], v[160:163], v[184:187], 0
	v_mfma_f32_16x16x32_bf16 v[88:91], v[168:171], v[184:187], 0
	v_mfma_f32_16x16x32_bf16 v[76:79], v[160:163], v[192:195], 0
	v_mfma_f32_16x16x32_bf16 v[72:75], v[168:171], v[192:195], 0
	v_mfma_f32_16x16x32_bf16 v[68:71], v[160:163], v[200:203], 0
	v_mfma_f32_16x16x32_bf16 v[64:67], v[168:171], v[200:203], 0
	v_mfma_f32_16x16x32_bf16 v[108:111], v[164:167], v[180:183], v[108:111]
	v_mfma_f32_16x16x32_bf16 v[104:107], v[172:175], v[180:183], v[104:107]
	v_mfma_f32_16x16x32_bf16 v[92:95], v[164:167], v[188:191], v[92:95]
	v_mfma_f32_16x16x32_bf16 v[88:91], v[172:175], v[188:191], v[88:91]
	v_mfma_f32_16x16x32_bf16 v[76:79], v[164:167], v[196:199], v[76:79]
	v_mfma_f32_16x16x32_bf16 v[72:75], v[172:175], v[196:199], v[72:75]
	v_mfma_f32_16x16x32_bf16 v[68:71], v[164:167], v[204:207], v[68:71]
	v_mfma_f32_16x16x32_bf16 v[64:67], v[172:175], v[204:207], v[64:67]
	s_barrier
	s_add_i32 s44, s44, s96
	s_mov_b32 m0, s44
	ds_read_b128 v[176:179], v143 offset:16384
	ds_read_b128 v[180:183], v143 offset:17408
	ds_read_b128 v[184:187], v143 offset:18432
	ds_read_b128 v[188:191], v143 offset:19456
	ds_read_b128 v[192:195], v143 offset:20480
	ds_read_b128 v[196:199], v143 offset:21504
	ds_read_b128 v[200:203], v143 offset:22528
	ds_read_b128 v[204:207], v143 offset:23552
	global_load_lds_dwordx4 v130, s[90:91]
	s_add_i32 m0, s44, 0x2000
	s_add_u32 s44, s90, 0x80000
	s_addc_u32 s45, s91, 0
	s_add_i32 s81, s81, s96
	global_load_lds_dwordx4 v134, s[90:91]
	s_mov_b32 m0, s81
	s_nop 0
	global_load_lds_dwordx4 v130, s[44:45]
	s_add_i32 m0, s81, 0x2000
	s_nop 0
	global_load_lds_dwordx4 v134, s[44:45]
	s_waitcnt vmcnt(6)
	s_waitcnt lgkmcnt(0)
	s_barrier
	v_mfma_f32_16x16x32_bf16 v[60:63], v[144:147], v[176:179], 0
	v_mfma_f32_16x16x32_bf16 v[56:59], v[152:155], v[176:179], 0
	v_mfma_f32_16x16x32_bf16 v[52:55], v[144:147], v[184:187], 0
	v_mfma_f32_16x16x32_bf16 v[48:51], v[152:155], v[184:187], 0
	v_mfma_f32_16x16x32_bf16 v[36:39], v[144:147], v[192:195], 0
	v_mfma_f32_16x16x32_bf16 v[32:35], v[152:155], v[192:195], 0
	v_mfma_f32_16x16x32_bf16 v[20:23], v[144:147], v[200:203], 0
	v_mfma_f32_16x16x32_bf16 v[16:19], v[152:155], v[200:203], 0
	v_mfma_f32_16x16x32_bf16 v[60:63], v[148:151], v[180:183], v[60:63]
	v_mfma_f32_16x16x32_bf16 v[56:59], v[156:159], v[180:183], v[56:59]
	v_mfma_f32_16x16x32_bf16 v[52:55], v[148:151], v[188:191], v[52:55]
	v_mfma_f32_16x16x32_bf16 v[48:51], v[156:159], v[188:191], v[48:51]
	v_mfma_f32_16x16x32_bf16 v[36:39], v[148:151], v[196:199], v[36:39]
	v_mfma_f32_16x16x32_bf16 v[32:35], v[156:159], v[196:199], v[32:35]
	v_mfma_f32_16x16x32_bf16 v[20:23], v[148:151], v[204:207], v[20:23]
	v_mfma_f32_16x16x32_bf16 v[16:19], v[156:159], v[204:207], v[16:19]
	v_mfma_f32_16x16x32_bf16 v[44:47], v[160:163], v[176:179], 0
	v_mfma_f32_16x16x32_bf16 v[40:43], v[168:171], v[176:179], 0
	v_mfma_f32_16x16x32_bf16 v[28:31], v[160:163], v[184:187], 0
	v_mfma_f32_16x16x32_bf16 v[24:27], v[168:171], v[184:187], 0
	v_mfma_f32_16x16x32_bf16 v[12:15], v[160:163], v[192:195], 0
	v_mfma_f32_16x16x32_bf16 v[8:11], v[168:171], v[192:195], 0
	v_mfma_f32_16x16x32_bf16 v[4:7], v[160:163], v[200:203], 0
	v_mfma_f32_16x16x32_bf16 v[0:3], v[168:171], v[200:203], 0
	v_mfma_f32_16x16x32_bf16 v[44:47], v[164:167], v[180:183], v[44:47]
	v_mfma_f32_16x16x32_bf16 v[40:43], v[172:175], v[180:183], v[40:43]
	v_mfma_f32_16x16x32_bf16 v[28:31], v[164:167], v[188:191], v[28:31]
	v_mfma_f32_16x16x32_bf16 v[24:27], v[172:175], v[188:191], v[24:27]
	v_mfma_f32_16x16x32_bf16 v[12:15], v[164:167], v[196:199], v[12:15]
	v_mfma_f32_16x16x32_bf16 v[8:11], v[172:175], v[196:199], v[8:11]
	v_mfma_f32_16x16x32_bf16 v[4:7], v[164:167], v[204:207], v[4:7]
	v_mfma_f32_16x16x32_bf16 v[0:3], v[172:175], v[204:207], v[0:3]
	s_barrier
	s_add_i32 s44, 0, 0x18000
	s_add_i32 s45, 0, 0x1c000
	ds_read_b128 v[144:147], v224
	ds_read_b128 v[148:151], v224 offset:1024
	ds_read_b128 v[152:155], v224 offset:2048
	ds_read_b128 v[156:159], v224 offset:3072
	ds_read_b128 v[160:163], v225
	ds_read_b128 v[164:167], v225 offset:1024
	ds_read_b128 v[168:171], v225 offset:2048
	ds_read_b128 v[172:175], v225 offset:3072
	ds_read_b128 v[176:179], v143 offset:32768
	ds_read_b128 v[180:183], v143 offset:33792
	ds_read_b128 v[184:187], v143 offset:34816
	ds_read_b128 v[188:191], v143 offset:35840
	ds_read_b128 v[192:195], v143 offset:36864
	ds_read_b128 v[196:199], v143 offset:37888
	ds_read_b128 v[200:203], v143 offset:38912
	ds_read_b128 v[204:207], v143 offset:39936
	s_mov_b32 m0, s57
	s_nop 0
	global_load_lds_dwordx4 v128, s[22:23]
	s_mov_b32 m0, s97
	s_nop 0
	global_load_lds_dwordx4 v132, s[22:23]
	s_mov_b32 m0, s93
	s_add_u32 s22, s22, 0x80000
	s_addc_u32 s23, s23, 0
	global_load_lds_dwordx4 v128, s[22:23]
	s_mov_b32 m0, s94
	s_nop 0
	global_load_lds_dwordx4 v132, s[22:23]
	s_waitcnt vmcnt(8)
	s_waitcnt lgkmcnt(0)
	s_barrier
	v_mfma_f32_16x16x32_bf16 v[124:127], v[144:147], v[176:179], v[124:127]
	v_mfma_f32_16x16x32_bf16 v[120:123], v[152:155], v[176:179], v[120:123]
	v_mfma_f32_16x16x32_bf16 v[116:119], v[144:147], v[184:187], v[116:119]
	v_mfma_f32_16x16x32_bf16 v[112:115], v[152:155], v[184:187], v[112:115]
	v_mfma_f32_16x16x32_bf16 v[100:103], v[144:147], v[192:195], v[100:103]
	v_mfma_f32_16x16x32_bf16 v[96:99], v[152:155], v[192:195], v[96:99]
	v_mfma_f32_16x16x32_bf16 v[84:87], v[144:147], v[200:203], v[84:87]
	v_mfma_f32_16x16x32_bf16 v[80:83], v[152:155], v[200:203], v[80:83]
	v_mfma_f32_16x16x32_bf16 v[124:127], v[148:151], v[180:183], v[124:127]
	v_mfma_f32_16x16x32_bf16 v[120:123], v[156:159], v[180:183], v[120:123]
	v_mfma_f32_16x16x32_bf16 v[116:119], v[148:151], v[188:191], v[116:119]
	v_mfma_f32_16x16x32_bf16 v[112:115], v[156:159], v[188:191], v[112:115]
	v_mfma_f32_16x16x32_bf16 v[100:103], v[148:151], v[196:199], v[100:103]
	v_mfma_f32_16x16x32_bf16 v[96:99], v[156:159], v[196:199], v[96:99]
	v_mfma_f32_16x16x32_bf16 v[84:87], v[148:151], v[204:207], v[84:87]
	v_mfma_f32_16x16x32_bf16 v[80:83], v[156:159], v[204:207], v[80:83]
	v_mfma_f32_16x16x32_bf16 v[108:111], v[160:163], v[176:179], v[108:111]
	v_mfma_f32_16x16x32_bf16 v[104:107], v[168:171], v[176:179], v[104:107]
	v_mfma_f32_16x16x32_bf16 v[92:95], v[160:163], v[184:187], v[92:95]
	v_mfma_f32_16x16x32_bf16 v[88:91], v[168:171], v[184:187], v[88:91]
	v_mfma_f32_16x16x32_bf16 v[76:79], v[160:163], v[192:195], v[76:79]
	v_mfma_f32_16x16x32_bf16 v[72:75], v[168:171], v[192:195], v[72:75]
	v_mfma_f32_16x16x32_bf16 v[68:71], v[160:163], v[200:203], v[68:71]
	v_mfma_f32_16x16x32_bf16 v[64:67], v[168:171], v[200:203], v[64:67]
	v_mfma_f32_16x16x32_bf16 v[108:111], v[164:167], v[180:183], v[108:111]
	v_mfma_f32_16x16x32_bf16 v[104:107], v[172:175], v[180:183], v[104:107]
	v_mfma_f32_16x16x32_bf16 v[92:95], v[164:167], v[188:191], v[92:95]
	v_mfma_f32_16x16x32_bf16 v[88:91], v[172:175], v[188:191], v[88:91]
	v_mfma_f32_16x16x32_bf16 v[76:79], v[164:167], v[196:199], v[76:79]
	v_mfma_f32_16x16x32_bf16 v[72:75], v[172:175], v[196:199], v[72:75]
	v_mfma_f32_16x16x32_bf16 v[68:71], v[164:167], v[204:207], v[68:71]
	v_mfma_f32_16x16x32_bf16 v[64:67], v[172:175], v[204:207], v[64:67]
	s_barrier
	s_add_i32 s22, s44, s96
	s_add_i32 m0, s22, 0xffffff80
	ds_read_b128 v[176:179], v143 offset:49152
	ds_read_b128 v[180:183], v143 offset:50176
	ds_read_b128 v[184:187], v143 offset:51200
	ds_read_b128 v[188:191], v143 offset:52224
	ds_read_b128 v[192:195], v143 offset:53248
	ds_read_b128 v[196:199], v143 offset:54272
	ds_read_b128 v[200:203], v143 offset:55296
	ds_read_b128 v[204:207], v143 offset:56320
	global_load_lds_dwordx4 v130, s[90:91] offset:128
	s_add_i32 m0, s22, 0x1f80
	s_add_u32 s22, s90, 0x80080
	s_addc_u32 s23, s91, 0
	s_add_i32 s44, s45, s96
	global_load_lds_dwordx4 v134, s[90:91] offset:128
	s_mov_b32 m0, s44
	s_nop 0
	global_load_lds_dwordx4 v130, s[22:23]
	s_add_i32 m0, s44, 0x2000
	s_nop 0
	global_load_lds_dwordx4 v134, s[22:23]
	s_add_u32 s22, s88, 0xfff80080
	s_addc_u32 s23, s89, -1
	s_cmp_eq_u32 s43, 28
	s_cselect_b32 s23, s30, s23
	s_cselect_b32 s22, s31, s22
	s_add_i32 m0, s92, 0xffffff80
	s_nop 0
	global_load_lds_dwordx4 v128, s[22:23] offset:128
	s_add_i32 m0, s6, 0xffffff80
	s_nop 0
	global_load_lds_dwordx4 v132, s[22:23] offset:128
	s_waitcnt vmcnt(8)
	s_waitcnt lgkmcnt(0)
	s_barrier
	v_mfma_f32_16x16x32_bf16 v[60:63], v[144:147], v[176:179], v[60:63]
	v_mfma_f32_16x16x32_bf16 v[56:59], v[152:155], v[176:179], v[56:59]
	v_mfma_f32_16x16x32_bf16 v[52:55], v[144:147], v[184:187], v[52:55]
	v_mfma_f32_16x16x32_bf16 v[48:51], v[152:155], v[184:187], v[48:51]
	v_mfma_f32_16x16x32_bf16 v[36:39], v[144:147], v[192:195], v[36:39]
	v_mfma_f32_16x16x32_bf16 v[32:35], v[152:155], v[192:195], v[32:35]
	v_mfma_f32_16x16x32_bf16 v[20:23], v[144:147], v[200:203], v[20:23]
	v_mfma_f32_16x16x32_bf16 v[16:19], v[152:155], v[200:203], v[16:19]
	v_mfma_f32_16x16x32_bf16 v[60:63], v[148:151], v[180:183], v[60:63]
	v_mfma_f32_16x16x32_bf16 v[56:59], v[156:159], v[180:183], v[56:59]
	v_mfma_f32_16x16x32_bf16 v[52:55], v[148:151], v[188:191], v[52:55]
	v_mfma_f32_16x16x32_bf16 v[48:51], v[156:159], v[188:191], v[48:51]
	v_mfma_f32_16x16x32_bf16 v[36:39], v[148:151], v[196:199], v[36:39]
	v_mfma_f32_16x16x32_bf16 v[32:35], v[156:159], v[196:199], v[32:35]
	v_mfma_f32_16x16x32_bf16 v[20:23], v[148:151], v[204:207], v[20:23]
	v_mfma_f32_16x16x32_bf16 v[16:19], v[156:159], v[204:207], v[16:19]
	v_mfma_f32_16x16x32_bf16 v[44:47], v[160:163], v[176:179], v[44:47]
	v_mfma_f32_16x16x32_bf16 v[40:43], v[168:171], v[176:179], v[40:43]
	v_mfma_f32_16x16x32_bf16 v[28:31], v[160:163], v[184:187], v[28:31]
	v_mfma_f32_16x16x32_bf16 v[24:27], v[168:171], v[184:187], v[24:27]
	v_mfma_f32_16x16x32_bf16 v[12:15], v[160:163], v[192:195], v[12:15]
	v_mfma_f32_16x16x32_bf16 v[8:11], v[168:171], v[192:195], v[8:11]
	v_mfma_f32_16x16x32_bf16 v[4:7], v[160:163], v[200:203], v[4:7]
	v_mfma_f32_16x16x32_bf16 v[0:3], v[168:171], v[200:203], v[0:3]
	v_mfma_f32_16x16x32_bf16 v[44:47], v[164:167], v[180:183], v[44:47]
	v_mfma_f32_16x16x32_bf16 v[40:43], v[172:175], v[180:183], v[40:43]
	v_mfma_f32_16x16x32_bf16 v[28:31], v[164:167], v[188:191], v[28:31]
	v_mfma_f32_16x16x32_bf16 v[24:27], v[172:175], v[188:191], v[24:27]
	v_mfma_f32_16x16x32_bf16 v[12:15], v[164:167], v[196:199], v[12:15]
	v_mfma_f32_16x16x32_bf16 v[8:11], v[172:175], v[196:199], v[8:11]
	v_mfma_f32_16x16x32_bf16 v[4:7], v[164:167], v[204:207], v[4:7]
	v_mfma_f32_16x16x32_bf16 v[0:3], v[172:175], v[204:207], v[0:3]
	s_barrier
	s_add_i32 s43, s43, 2
	s_add_u32 s88, s88, 0x100
	s_addc_u32 s89, s89, 0
	s_add_u32 s41, s41, 0x100
	s_addc_u32 s42, s42, 0
	s_cmp_gt_u32 s43, 29
	s_cbranch_scc0 .LBB0_631
.LBB0_631:
	s_add_u32 s22, s88, 0xfff80080
	s_addc_u32 s23, s89, -1
	s_add_i32 s44, 0, 0x10000
	s_cmp_eq_u32 s43, 28
	s_cselect_b32 s23, s30, s23
	s_cselect_b32 s22, s31, s22
	s_cselect_b32 s91, s38, s42
	s_cselect_b32 s90, s39, s41
	s_add_i32 s81, 0, 0x14000
	ds_read_b128 v[144:147], v222
	ds_read_b128 v[148:151], v222 offset:1024
	ds_read_b128 v[152:155], v222 offset:2048
	ds_read_b128 v[156:159], v222 offset:3072
	ds_read_b128 v[160:163], v223
	ds_read_b128 v[164:167], v223 offset:1024
	ds_read_b128 v[168:171], v223 offset:2048
	ds_read_b128 v[172:175], v223 offset:3072
	s_add_i32 m0, s57, 0xc000
	ds_read_b128 v[176:179], v143
	ds_read_b128 v[180:183], v143 offset:1024
	ds_read_b128 v[184:187], v143 offset:2048
	ds_read_b128 v[188:191], v143 offset:3072
	ds_read_b128 v[192:195], v143 offset:4096
	ds_read_b128 v[196:199], v143 offset:5120
	ds_read_b128 v[200:203], v143 offset:6144
	ds_read_b128 v[204:207], v143 offset:7168
	global_load_lds_dwordx4 v136, s[88:89]
	s_add_i32 m0, s57, 0xe000
	s_nop 0
	global_load_lds_dwordx4 v138, s[88:89]
	s_waitcnt vmcnt(8)
	s_waitcnt lgkmcnt(0)
	s_barrier
	v_mfma_f32_16x16x32_bf16 v[124:127], v[144:147], v[176:179], v[124:127]
	v_mfma_f32_16x16x32_bf16 v[120:123], v[152:155], v[176:179], v[120:123]
	v_mfma_f32_16x16x32_bf16 v[116:119], v[144:147], v[184:187], v[116:119]
	v_mfma_f32_16x16x32_bf16 v[112:115], v[152:155], v[184:187], v[112:115]
	v_mfma_f32_16x16x32_bf16 v[100:103], v[144:147], v[192:195], v[100:103]
	v_mfma_f32_16x16x32_bf16 v[96:99], v[152:155], v[192:195], v[96:99]
	v_mfma_f32_16x16x32_bf16 v[84:87], v[144:147], v[200:203], v[84:87]
	v_mfma_f32_16x16x32_bf16 v[80:83], v[152:155], v[200:203], v[80:83]
	v_mfma_f32_16x16x32_bf16 v[124:127], v[148:151], v[180:183], v[124:127]
	v_mfma_f32_16x16x32_bf16 v[120:123], v[156:159], v[180:183], v[120:123]
	v_mfma_f32_16x16x32_bf16 v[116:119], v[148:151], v[188:191], v[116:119]
	v_mfma_f32_16x16x32_bf16 v[112:115], v[156:159], v[188:191], v[112:115]
	v_mfma_f32_16x16x32_bf16 v[100:103], v[148:151], v[196:199], v[100:103]
	v_mfma_f32_16x16x32_bf16 v[96:99], v[156:159], v[196:199], v[96:99]
	v_mfma_f32_16x16x32_bf16 v[84:87], v[148:151], v[204:207], v[84:87]
	v_mfma_f32_16x16x32_bf16 v[80:83], v[156:159], v[204:207], v[80:83]
	v_mfma_f32_16x16x32_bf16 v[108:111], v[160:163], v[176:179], v[108:111]
	v_mfma_f32_16x16x32_bf16 v[104:107], v[168:171], v[176:179], v[104:107]
	v_mfma_f32_16x16x32_bf16 v[92:95], v[160:163], v[184:187], v[92:95]
	v_mfma_f32_16x16x32_bf16 v[88:91], v[168:171], v[184:187], v[88:91]
	v_mfma_f32_16x16x32_bf16 v[76:79], v[160:163], v[192:195], v[76:79]
	v_mfma_f32_16x16x32_bf16 v[72:75], v[168:171], v[192:195], v[72:75]
	v_mfma_f32_16x16x32_bf16 v[68:71], v[160:163], v[200:203], v[68:71]
	v_mfma_f32_16x16x32_bf16 v[64:67], v[168:171], v[200:203], v[64:67]
	v_mfma_f32_16x16x32_bf16 v[108:111], v[164:167], v[180:183], v[108:111]
	v_mfma_f32_16x16x32_bf16 v[104:107], v[172:175], v[180:183], v[104:107]
	v_mfma_f32_16x16x32_bf16 v[92:95], v[164:167], v[188:191], v[92:95]
	v_mfma_f32_16x16x32_bf16 v[88:91], v[172:175], v[188:191], v[88:91]
	v_mfma_f32_16x16x32_bf16 v[76:79], v[164:167], v[196:199], v[76:79]
	v_mfma_f32_16x16x32_bf16 v[72:75], v[172:175], v[196:199], v[72:75]
	v_mfma_f32_16x16x32_bf16 v[68:71], v[164:167], v[204:207], v[68:71]
	v_mfma_f32_16x16x32_bf16 v[64:67], v[172:175], v[204:207], v[64:67]
	s_barrier
	s_add_i32 s44, s44, s96
	s_mov_b32 m0, s44
	ds_read_b128 v[176:179], v143 offset:16384
	ds_read_b128 v[180:183], v143 offset:17408
	ds_read_b128 v[184:187], v143 offset:18432
	ds_read_b128 v[188:191], v143 offset:19456
	ds_read_b128 v[192:195], v143 offset:20480
	ds_read_b128 v[196:199], v143 offset:21504
	ds_read_b128 v[200:203], v143 offset:22528
	ds_read_b128 v[204:207], v143 offset:23552
	global_load_lds_dwordx4 v130, s[90:91]
	s_add_i32 m0, s44, 0x2000
	s_add_u32 s44, s90, 0x80000
	s_addc_u32 s45, s91, 0
	s_add_i32 s81, s81, s96
	global_load_lds_dwordx4 v134, s[90:91]
	s_mov_b32 m0, s81
	s_nop 0
	global_load_lds_dwordx4 v130, s[44:45]
	s_add_i32 m0, s81, 0x2000
	s_nop 0
	global_load_lds_dwordx4 v134, s[44:45]
	s_waitcnt vmcnt(6)
	s_waitcnt lgkmcnt(0)
	s_barrier
	v_mfma_f32_16x16x32_bf16 v[60:63], v[144:147], v[176:179], v[60:63]
	v_mfma_f32_16x16x32_bf16 v[56:59], v[152:155], v[176:179], v[56:59]
	v_mfma_f32_16x16x32_bf16 v[52:55], v[144:147], v[184:187], v[52:55]
	v_mfma_f32_16x16x32_bf16 v[48:51], v[152:155], v[184:187], v[48:51]
	v_mfma_f32_16x16x32_bf16 v[36:39], v[144:147], v[192:195], v[36:39]
	v_mfma_f32_16x16x32_bf16 v[32:35], v[152:155], v[192:195], v[32:35]
	v_mfma_f32_16x16x32_bf16 v[20:23], v[144:147], v[200:203], v[20:23]
	v_mfma_f32_16x16x32_bf16 v[16:19], v[152:155], v[200:203], v[16:19]
	v_mfma_f32_16x16x32_bf16 v[60:63], v[148:151], v[180:183], v[60:63]
	v_mfma_f32_16x16x32_bf16 v[56:59], v[156:159], v[180:183], v[56:59]
	v_mfma_f32_16x16x32_bf16 v[52:55], v[148:151], v[188:191], v[52:55]
	v_mfma_f32_16x16x32_bf16 v[48:51], v[156:159], v[188:191], v[48:51]
	v_mfma_f32_16x16x32_bf16 v[36:39], v[148:151], v[196:199], v[36:39]
	v_mfma_f32_16x16x32_bf16 v[32:35], v[156:159], v[196:199], v[32:35]
	v_mfma_f32_16x16x32_bf16 v[20:23], v[148:151], v[204:207], v[20:23]
	v_mfma_f32_16x16x32_bf16 v[16:19], v[156:159], v[204:207], v[16:19]
	v_mfma_f32_16x16x32_bf16 v[44:47], v[160:163], v[176:179], v[44:47]
	v_mfma_f32_16x16x32_bf16 v[40:43], v[168:171], v[176:179], v[40:43]
	v_mfma_f32_16x16x32_bf16 v[28:31], v[160:163], v[184:187], v[28:31]
	v_mfma_f32_16x16x32_bf16 v[24:27], v[168:171], v[184:187], v[24:27]
	v_mfma_f32_16x16x32_bf16 v[12:15], v[160:163], v[192:195], v[12:15]
	v_mfma_f32_16x16x32_bf16 v[8:11], v[168:171], v[192:195], v[8:11]
	v_mfma_f32_16x16x32_bf16 v[4:7], v[160:163], v[200:203], v[4:7]
	v_mfma_f32_16x16x32_bf16 v[0:3], v[168:171], v[200:203], v[0:3]
	v_mfma_f32_16x16x32_bf16 v[44:47], v[164:167], v[180:183], v[44:47]
	v_mfma_f32_16x16x32_bf16 v[40:43], v[172:175], v[180:183], v[40:43]
	v_mfma_f32_16x16x32_bf16 v[28:31], v[164:167], v[188:191], v[28:31]
	v_mfma_f32_16x16x32_bf16 v[24:27], v[172:175], v[188:191], v[24:27]
	v_mfma_f32_16x16x32_bf16 v[12:15], v[164:167], v[196:199], v[12:15]
	v_mfma_f32_16x16x32_bf16 v[8:11], v[172:175], v[196:199], v[8:11]
	v_mfma_f32_16x16x32_bf16 v[4:7], v[164:167], v[204:207], v[4:7]
	v_mfma_f32_16x16x32_bf16 v[0:3], v[172:175], v[204:207], v[0:3]
	s_barrier
	s_add_i32 s44, 0, 0x18000
	s_add_i32 s45, 0, 0x1c000
	ds_read_b128 v[144:147], v224
	ds_read_b128 v[148:151], v224 offset:1024
	ds_read_b128 v[152:155], v224 offset:2048
	ds_read_b128 v[156:159], v224 offset:3072
	ds_read_b128 v[160:163], v225
	ds_read_b128 v[164:167], v225 offset:1024
	ds_read_b128 v[168:171], v225 offset:2048
	ds_read_b128 v[172:175], v225 offset:3072
	ds_read_b128 v[176:179], v143 offset:32768
	ds_read_b128 v[180:183], v143 offset:33792
	ds_read_b128 v[184:187], v143 offset:34816
	ds_read_b128 v[188:191], v143 offset:35840
	ds_read_b128 v[192:195], v143 offset:36864
	ds_read_b128 v[196:199], v143 offset:37888
	ds_read_b128 v[200:203], v143 offset:38912
	ds_read_b128 v[204:207], v143 offset:39936
	s_mov_b32 m0, s57
	s_nop 0
	global_load_lds_dwordx4 v128, s[22:23]
	s_mov_b32 m0, s97
	s_nop 0
	global_load_lds_dwordx4 v132, s[22:23]
	s_mov_b32 m0, s93
	s_add_u32 s22, s22, 0x80000
	s_addc_u32 s23, s23, 0
	global_load_lds_dwordx4 v128, s[22:23]
	s_mov_b32 m0, s94
	s_nop 0
	global_load_lds_dwordx4 v132, s[22:23]
	s_waitcnt vmcnt(8)
	s_waitcnt lgkmcnt(0)
	s_barrier
	v_mfma_f32_16x16x32_bf16 v[124:127], v[144:147], v[176:179], v[124:127]
	v_mfma_f32_16x16x32_bf16 v[120:123], v[152:155], v[176:179], v[120:123]
	v_mfma_f32_16x16x32_bf16 v[116:119], v[144:147], v[184:187], v[116:119]
	v_mfma_f32_16x16x32_bf16 v[112:115], v[152:155], v[184:187], v[112:115]
	v_mfma_f32_16x16x32_bf16 v[100:103], v[144:147], v[192:195], v[100:103]
	v_mfma_f32_16x16x32_bf16 v[96:99], v[152:155], v[192:195], v[96:99]
	v_mfma_f32_16x16x32_bf16 v[84:87], v[144:147], v[200:203], v[84:87]
	v_mfma_f32_16x16x32_bf16 v[80:83], v[152:155], v[200:203], v[80:83]
	v_mfma_f32_16x16x32_bf16 v[124:127], v[148:151], v[180:183], v[124:127]
	v_mfma_f32_16x16x32_bf16 v[120:123], v[156:159], v[180:183], v[120:123]
	v_mfma_f32_16x16x32_bf16 v[116:119], v[148:151], v[188:191], v[116:119]
	v_mfma_f32_16x16x32_bf16 v[112:115], v[156:159], v[188:191], v[112:115]
	v_mfma_f32_16x16x32_bf16 v[100:103], v[148:151], v[196:199], v[100:103]
	v_mfma_f32_16x16x32_bf16 v[96:99], v[156:159], v[196:199], v[96:99]
	v_mfma_f32_16x16x32_bf16 v[84:87], v[148:151], v[204:207], v[84:87]
	v_mfma_f32_16x16x32_bf16 v[80:83], v[156:159], v[204:207], v[80:83]
	v_mfma_f32_16x16x32_bf16 v[108:111], v[160:163], v[176:179], v[108:111]
	v_mfma_f32_16x16x32_bf16 v[104:107], v[168:171], v[176:179], v[104:107]
	v_mfma_f32_16x16x32_bf16 v[92:95], v[160:163], v[184:187], v[92:95]
	v_mfma_f32_16x16x32_bf16 v[88:91], v[168:171], v[184:187], v[88:91]
	v_mfma_f32_16x16x32_bf16 v[76:79], v[160:163], v[192:195], v[76:79]
	v_mfma_f32_16x16x32_bf16 v[72:75], v[168:171], v[192:195], v[72:75]
	v_mfma_f32_16x16x32_bf16 v[68:71], v[160:163], v[200:203], v[68:71]
	v_mfma_f32_16x16x32_bf16 v[64:67], v[168:171], v[200:203], v[64:67]
	v_mfma_f32_16x16x32_bf16 v[108:111], v[164:167], v[180:183], v[108:111]
	v_mfma_f32_16x16x32_bf16 v[104:107], v[172:175], v[180:183], v[104:107]
	v_mfma_f32_16x16x32_bf16 v[92:95], v[164:167], v[188:191], v[92:95]
	v_mfma_f32_16x16x32_bf16 v[88:91], v[172:175], v[188:191], v[88:91]
	v_mfma_f32_16x16x32_bf16 v[76:79], v[164:167], v[196:199], v[76:79]
	v_mfma_f32_16x16x32_bf16 v[72:75], v[172:175], v[196:199], v[72:75]
	v_mfma_f32_16x16x32_bf16 v[68:71], v[164:167], v[204:207], v[68:71]
	v_mfma_f32_16x16x32_bf16 v[64:67], v[172:175], v[204:207], v[64:67]
	s_barrier
	s_add_i32 s22, s44, s96
	s_add_i32 m0, s22, 0xffffff80
	ds_read_b128 v[176:179], v143 offset:49152
	ds_read_b128 v[180:183], v143 offset:50176
	ds_read_b128 v[184:187], v143 offset:51200
	ds_read_b128 v[188:191], v143 offset:52224
	ds_read_b128 v[192:195], v143 offset:53248
	ds_read_b128 v[196:199], v143 offset:54272
	ds_read_b128 v[200:203], v143 offset:55296
	ds_read_b128 v[204:207], v143 offset:56320
	global_load_lds_dwordx4 v130, s[90:91] offset:128
	s_add_i32 m0, s22, 0x1f80
	s_add_u32 s22, s90, 0x80080
	s_addc_u32 s23, s91, 0
	s_add_i32 s44, s45, s96
	global_load_lds_dwordx4 v134, s[90:91] offset:128
	s_mov_b32 m0, s44
	s_nop 0
	global_load_lds_dwordx4 v130, s[22:23]
	s_add_i32 m0, s44, 0x2000
	s_nop 0
	global_load_lds_dwordx4 v134, s[22:23]
	s_add_u32 s22, s88, 0xfff80080
	s_addc_u32 s23, s89, -1
	s_cmp_eq_u32 s43, 28
	s_cselect_b32 s23, s30, s23
	s_cselect_b32 s22, s31, s22
	s_add_i32 m0, s92, 0xffffff80
	s_nop 0
	global_load_lds_dwordx4 v128, s[22:23] offset:128
	s_add_i32 m0, s6, 0xffffff80
	s_nop 0
	global_load_lds_dwordx4 v132, s[22:23] offset:128
	s_waitcnt vmcnt(8)
	s_waitcnt lgkmcnt(0)
	s_barrier
	v_mfma_f32_16x16x32_bf16 v[60:63], v[144:147], v[176:179], v[60:63]
	v_mfma_f32_16x16x32_bf16 v[56:59], v[152:155], v[176:179], v[56:59]
	v_mfma_f32_16x16x32_bf16 v[52:55], v[144:147], v[184:187], v[52:55]
	v_mfma_f32_16x16x32_bf16 v[48:51], v[152:155], v[184:187], v[48:51]
	v_mfma_f32_16x16x32_bf16 v[36:39], v[144:147], v[192:195], v[36:39]
	v_mfma_f32_16x16x32_bf16 v[32:35], v[152:155], v[192:195], v[32:35]
	v_mfma_f32_16x16x32_bf16 v[20:23], v[144:147], v[200:203], v[20:23]
	v_mfma_f32_16x16x32_bf16 v[16:19], v[152:155], v[200:203], v[16:19]
	v_mfma_f32_16x16x32_bf16 v[60:63], v[148:151], v[180:183], v[60:63]
	v_mfma_f32_16x16x32_bf16 v[56:59], v[156:159], v[180:183], v[56:59]
	v_mfma_f32_16x16x32_bf16 v[52:55], v[148:151], v[188:191], v[52:55]
	v_mfma_f32_16x16x32_bf16 v[48:51], v[156:159], v[188:191], v[48:51]
	v_mfma_f32_16x16x32_bf16 v[36:39], v[148:151], v[196:199], v[36:39]
	v_mfma_f32_16x16x32_bf16 v[32:35], v[156:159], v[196:199], v[32:35]
	v_mfma_f32_16x16x32_bf16 v[20:23], v[148:151], v[204:207], v[20:23]
	v_mfma_f32_16x16x32_bf16 v[16:19], v[156:159], v[204:207], v[16:19]
	v_mfma_f32_16x16x32_bf16 v[44:47], v[160:163], v[176:179], v[44:47]
	v_mfma_f32_16x16x32_bf16 v[40:43], v[168:171], v[176:179], v[40:43]
	v_mfma_f32_16x16x32_bf16 v[28:31], v[160:163], v[184:187], v[28:31]
	v_mfma_f32_16x16x32_bf16 v[24:27], v[168:171], v[184:187], v[24:27]
	v_mfma_f32_16x16x32_bf16 v[12:15], v[160:163], v[192:195], v[12:15]
	v_mfma_f32_16x16x32_bf16 v[8:11], v[168:171], v[192:195], v[8:11]
	v_mfma_f32_16x16x32_bf16 v[4:7], v[160:163], v[200:203], v[4:7]
	v_mfma_f32_16x16x32_bf16 v[0:3], v[168:171], v[200:203], v[0:3]
	v_mfma_f32_16x16x32_bf16 v[44:47], v[164:167], v[180:183], v[44:47]
	v_mfma_f32_16x16x32_bf16 v[40:43], v[172:175], v[180:183], v[40:43]
	v_mfma_f32_16x16x32_bf16 v[28:31], v[164:167], v[188:191], v[28:31]
	v_mfma_f32_16x16x32_bf16 v[24:27], v[172:175], v[188:191], v[24:27]
	v_mfma_f32_16x16x32_bf16 v[12:15], v[164:167], v[196:199], v[12:15]
	v_mfma_f32_16x16x32_bf16 v[8:11], v[172:175], v[196:199], v[8:11]
	v_mfma_f32_16x16x32_bf16 v[4:7], v[164:167], v[204:207], v[4:7]
	v_mfma_f32_16x16x32_bf16 v[0:3], v[172:175], v[204:207], v[0:3]
	s_barrier
	s_add_i32 s43, s43, 2
	s_add_u32 s88, s88, 0x100
	s_addc_u32 s89, s89, 0
	s_add_u32 s41, s41, 0x100
	s_addc_u32 s42, s42, 0
	s_cmp_gt_u32 s43, 29
	s_cbranch_scc0 .LBB0_631
	s_cmp_eq_u32 s40, 0
	s_cselect_b64 s[30:31], -1, 0
	s_cmp_lg_u32 s40, 0
	s_mov_b64 s[38:39], -1
	s_cbranch_scc0 .LBB0_634
	s_lshl_b32 s22, s80, 8
	s_or_b32 s22, s22, s53
	s_ashr_i32 s22, s22, 6
	s_mov_b64 s[38:39], 0

.LBB0_1259:
	s_add_u32 s22, s92, s76
	s_addc_u32 s23, s93, s77
	s_add_u32 s80, s96, s76
	s_addc_u32 s81, s97, s77
	s_cmp_eq_u32 s44, 0
	s_cselect_b32 s23, s15, s23
	s_cselect_b32 s22, s91, s22
	s_cselect_b32 vcc_hi, s89, s81
	s_cselect_b32 vcc_lo, s8, s80
	s_add_i32 s80, 0, 0x10000
	s_add_i32 s83, 0, 0x14000
	ds_read_b128 v[142:145], v222
	ds_read_b128 v[146:149], v222 offset:1024
	ds_read_b128 v[150:153], v222 offset:2048
	ds_read_b128 v[154:157], v222 offset:3072
	ds_read_b128 v[158:161], v223
	ds_read_b128 v[162:165], v223 offset:1024
	ds_read_b128 v[166:169], v223 offset:2048
	ds_read_b128 v[170:173], v223 offset:3072
	s_add_i32 m0, s45, 0xc000
	ds_read_b128 v[174:177], v140
	ds_read_b128 v[178:181], v140 offset:1024
	ds_read_b128 v[182:185], v140 offset:2048
	ds_read_b128 v[186:189], v140 offset:3072
	ds_read_b128 v[190:193], v140 offset:4096
	ds_read_b128 v[194:197], v140 offset:5120
	ds_read_b128 v[198:201], v140 offset:6144
	ds_read_b128 v[202:205], v140 offset:7168
	global_load_lds_dwordx4 v136, s[92:93]
	s_add_i32 m0, s45, 0xe000
	s_nop 0
	global_load_lds_dwordx4 v134, s[92:93]
	s_waitcnt vmcnt(8)
	s_waitcnt lgkmcnt(0)
	s_barrier
	v_mfma_f32_16x16x32_bf16 v[124:127], v[142:145], v[174:177], v[124:127]
	v_mfma_f32_16x16x32_bf16 v[120:123], v[150:153], v[174:177], v[120:123]
	v_mfma_f32_16x16x32_bf16 v[108:111], v[142:145], v[182:185], v[108:111]
	v_mfma_f32_16x16x32_bf16 v[104:107], v[150:153], v[182:185], v[104:107]
	v_mfma_f32_16x16x32_bf16 v[92:95], v[142:145], v[190:193], v[92:95]
	v_mfma_f32_16x16x32_bf16 v[88:91], v[150:153], v[190:193], v[88:91]
	v_mfma_f32_16x16x32_bf16 v[76:79], v[142:145], v[198:201], v[76:79]
	v_mfma_f32_16x16x32_bf16 v[72:75], v[150:153], v[198:201], v[72:75]
	v_mfma_f32_16x16x32_bf16 v[124:127], v[146:149], v[178:181], v[124:127]
	v_mfma_f32_16x16x32_bf16 v[120:123], v[154:157], v[178:181], v[120:123]
	v_mfma_f32_16x16x32_bf16 v[108:111], v[146:149], v[186:189], v[108:111]
	v_mfma_f32_16x16x32_bf16 v[104:107], v[154:157], v[186:189], v[104:107]
	v_mfma_f32_16x16x32_bf16 v[92:95], v[146:149], v[194:197], v[92:95]
	v_mfma_f32_16x16x32_bf16 v[88:91], v[154:157], v[194:197], v[88:91]
	v_mfma_f32_16x16x32_bf16 v[76:79], v[146:149], v[202:205], v[76:79]
	v_mfma_f32_16x16x32_bf16 v[72:75], v[154:157], v[202:205], v[72:75]
	v_mfma_f32_16x16x32_bf16 v[116:119], v[158:161], v[174:177], v[116:119]
	v_mfma_f32_16x16x32_bf16 v[112:115], v[166:169], v[174:177], v[112:115]
	v_mfma_f32_16x16x32_bf16 v[100:103], v[158:161], v[182:185], v[100:103]
	v_mfma_f32_16x16x32_bf16 v[96:99], v[166:169], v[182:185], v[96:99]
	v_mfma_f32_16x16x32_bf16 v[84:87], v[158:161], v[190:193], v[84:87]
	v_mfma_f32_16x16x32_bf16 v[80:83], v[166:169], v[190:193], v[80:83]
	v_mfma_f32_16x16x32_bf16 v[68:71], v[158:161], v[198:201], v[68:71]
	v_mfma_f32_16x16x32_bf16 v[64:67], v[166:169], v[198:201], v[64:67]
	v_mfma_f32_16x16x32_bf16 v[116:119], v[162:165], v[178:181], v[116:119]
	v_mfma_f32_16x16x32_bf16 v[112:115], v[170:173], v[178:181], v[112:115]
	v_mfma_f32_16x16x32_bf16 v[100:103], v[162:165], v[186:189], v[100:103]
	v_mfma_f32_16x16x32_bf16 v[96:99], v[170:173], v[186:189], v[96:99]
	v_mfma_f32_16x16x32_bf16 v[84:87], v[162:165], v[194:197], v[84:87]
	v_mfma_f32_16x16x32_bf16 v[80:83], v[170:173], v[194:197], v[80:83]
	v_mfma_f32_16x16x32_bf16 v[68:71], v[162:165], v[202:205], v[68:71]
	v_mfma_f32_16x16x32_bf16 v[64:67], v[170:173], v[202:205], v[64:67]
	s_barrier
	s_add_i32 s80, s80, s43
	s_mov_b32 m0, s80
	ds_read_b128 v[174:177], v140 offset:16384
	ds_read_b128 v[178:181], v140 offset:17408
	ds_read_b128 v[182:185], v140 offset:18432
	ds_read_b128 v[186:189], v140 offset:19456
	ds_read_b128 v[190:193], v140 offset:20480
	ds_read_b128 v[194:197], v140 offset:21504
	ds_read_b128 v[198:201], v140 offset:22528
	ds_read_b128 v[202:205], v140 offset:23552
	global_load_lds_dwordx4 v208, vcc
	s_add_i32 m0, s80, 0x2000
	s_add_u32 s80, vcc_lo, 0x80000
	s_addc_u32 s81, vcc_hi, 0
	s_add_i32 s83, s83, s43
	global_load_lds_dwordx4 v128, vcc
	s_mov_b32 m0, s83
	s_nop 0
	global_load_lds_dwordx4 v208, s[80:81]
	s_add_i32 m0, s83, 0x2000
	s_nop 0
	global_load_lds_dwordx4 v128, s[80:81]
	s_waitcnt vmcnt(6)
	s_waitcnt lgkmcnt(0)
	s_barrier
	v_mfma_f32_16x16x32_bf16 v[60:63], v[142:145], v[174:177], v[60:63]
	v_mfma_f32_16x16x32_bf16 v[56:59], v[150:153], v[174:177], v[56:59]
	v_mfma_f32_16x16x32_bf16 v[44:47], v[142:145], v[182:185], v[44:47]
	v_mfma_f32_16x16x32_bf16 v[40:43], v[150:153], v[182:185], v[40:43]
	v_mfma_f32_16x16x32_bf16 v[28:31], v[142:145], v[190:193], v[28:31]
	v_mfma_f32_16x16x32_bf16 v[24:27], v[150:153], v[190:193], v[24:27]
	v_mfma_f32_16x16x32_bf16 v[12:15], v[142:145], v[198:201], v[12:15]
	v_mfma_f32_16x16x32_bf16 v[8:11], v[150:153], v[198:201], v[8:11]
	v_mfma_f32_16x16x32_bf16 v[60:63], v[146:149], v[178:181], v[60:63]
	v_mfma_f32_16x16x32_bf16 v[56:59], v[154:157], v[178:181], v[56:59]
	v_mfma_f32_16x16x32_bf16 v[44:47], v[146:149], v[186:189], v[44:47]
	v_mfma_f32_16x16x32_bf16 v[40:43], v[154:157], v[186:189], v[40:43]
	v_mfma_f32_16x16x32_bf16 v[28:31], v[146:149], v[194:197], v[28:31]
	v_mfma_f32_16x16x32_bf16 v[24:27], v[154:157], v[194:197], v[24:27]
	v_mfma_f32_16x16x32_bf16 v[12:15], v[146:149], v[202:205], v[12:15]
	v_mfma_f32_16x16x32_bf16 v[8:11], v[154:157], v[202:205], v[8:11]
	v_mfma_f32_16x16x32_bf16 v[52:55], v[158:161], v[174:177], v[52:55]
	v_mfma_f32_16x16x32_bf16 v[48:51], v[166:169], v[174:177], v[48:51]
	v_mfma_f32_16x16x32_bf16 v[36:39], v[158:161], v[182:185], v[36:39]
	v_mfma_f32_16x16x32_bf16 v[32:35], v[166:169], v[182:185], v[32:35]
	v_mfma_f32_16x16x32_bf16 v[20:23], v[158:161], v[190:193], v[20:23]
	v_mfma_f32_16x16x32_bf16 v[16:19], v[166:169], v[190:193], v[16:19]
	v_mfma_f32_16x16x32_bf16 v[4:7], v[158:161], v[198:201], v[4:7]
	v_mfma_f32_16x16x32_bf16 v[0:3], v[166:169], v[198:201], v[0:3]
	v_mfma_f32_16x16x32_bf16 v[52:55], v[162:165], v[178:181], v[52:55]
	v_mfma_f32_16x16x32_bf16 v[48:51], v[170:173], v[178:181], v[48:51]
	v_mfma_f32_16x16x32_bf16 v[36:39], v[162:165], v[186:189], v[36:39]
	v_mfma_f32_16x16x32_bf16 v[32:35], v[170:173], v[186:189], v[32:35]
	v_mfma_f32_16x16x32_bf16 v[20:23], v[162:165], v[194:197], v[20:23]
	v_mfma_f32_16x16x32_bf16 v[16:19], v[170:173], v[194:197], v[16:19]
	v_mfma_f32_16x16x32_bf16 v[4:7], v[162:165], v[202:205], v[4:7]
	v_mfma_f32_16x16x32_bf16 v[0:3], v[170:173], v[202:205], v[0:3]
	s_barrier
	s_add_i32 s80, 0, 0x18000
	s_add_i32 s81, 0, 0x1c000
	ds_read_b128 v[142:145], v224
	ds_read_b128 v[146:149], v224 offset:1024
	ds_read_b128 v[150:153], v224 offset:2048
	ds_read_b128 v[154:157], v224 offset:3072
	ds_read_b128 v[158:161], v225
	ds_read_b128 v[162:165], v225 offset:1024
	ds_read_b128 v[166:169], v225 offset:2048
	ds_read_b128 v[170:173], v225 offset:3072
	ds_read_b128 v[174:177], v140 offset:32768
	ds_read_b128 v[178:181], v140 offset:33792
	ds_read_b128 v[182:185], v140 offset:34816
	ds_read_b128 v[186:189], v140 offset:35840
	ds_read_b128 v[190:193], v140 offset:36864
	ds_read_b128 v[194:197], v140 offset:37888
	ds_read_b128 v[198:201], v140 offset:38912
	ds_read_b128 v[202:205], v140 offset:39936
	s_mov_b32 m0, s45
	s_nop 0
	global_load_lds_dwordx4 v208, s[22:23]
	s_mov_b32 m0, s52
	s_nop 0
	global_load_lds_dwordx4 v128, s[22:23]
	s_mov_b32 m0, s53
	s_add_u32 s22, s22, 0x80000
	s_addc_u32 s23, s23, 0
	global_load_lds_dwordx4 v208, s[22:23]
	s_mov_b32 m0, s85
	s_nop 0
	global_load_lds_dwordx4 v128, s[22:23]
	s_waitcnt vmcnt(8)
	s_waitcnt lgkmcnt(0)
	s_barrier
	v_mfma_f32_16x16x32_bf16 v[124:127], v[142:145], v[174:177], v[124:127]
	v_mfma_f32_16x16x32_bf16 v[120:123], v[150:153], v[174:177], v[120:123]
	v_mfma_f32_16x16x32_bf16 v[108:111], v[142:145], v[182:185], v[108:111]
	v_mfma_f32_16x16x32_bf16 v[104:107], v[150:153], v[182:185], v[104:107]
	v_mfma_f32_16x16x32_bf16 v[92:95], v[142:145], v[190:193], v[92:95]
	v_mfma_f32_16x16x32_bf16 v[88:91], v[150:153], v[190:193], v[88:91]
	v_mfma_f32_16x16x32_bf16 v[76:79], v[142:145], v[198:201], v[76:79]
	v_mfma_f32_16x16x32_bf16 v[72:75], v[150:153], v[198:201], v[72:75]
	v_mfma_f32_16x16x32_bf16 v[124:127], v[146:149], v[178:181], v[124:127]
	v_mfma_f32_16x16x32_bf16 v[120:123], v[154:157], v[178:181], v[120:123]
	v_mfma_f32_16x16x32_bf16 v[108:111], v[146:149], v[186:189], v[108:111]
	v_mfma_f32_16x16x32_bf16 v[104:107], v[154:157], v[186:189], v[104:107]
	v_mfma_f32_16x16x32_bf16 v[92:95], v[146:149], v[194:197], v[92:95]
	v_mfma_f32_16x16x32_bf16 v[88:91], v[154:157], v[194:197], v[88:91]
	v_mfma_f32_16x16x32_bf16 v[76:79], v[146:149], v[202:205], v[76:79]
	v_mfma_f32_16x16x32_bf16 v[72:75], v[154:157], v[202:205], v[72:75]
	v_mfma_f32_16x16x32_bf16 v[116:119], v[158:161], v[174:177], v[116:119]
	v_mfma_f32_16x16x32_bf16 v[112:115], v[166:169], v[174:177], v[112:115]
	v_mfma_f32_16x16x32_bf16 v[100:103], v[158:161], v[182:185], v[100:103]
	v_mfma_f32_16x16x32_bf16 v[96:99], v[166:169], v[182:185], v[96:99]
	v_mfma_f32_16x16x32_bf16 v[84:87], v[158:161], v[190:193], v[84:87]
	v_mfma_f32_16x16x32_bf16 v[80:83], v[166:169], v[190:193], v[80:83]
	v_mfma_f32_16x16x32_bf16 v[68:71], v[158:161], v[198:201], v[68:71]
	v_mfma_f32_16x16x32_bf16 v[64:67], v[166:169], v[198:201], v[64:67]
	v_mfma_f32_16x16x32_bf16 v[116:119], v[162:165], v[178:181], v[116:119]
	v_mfma_f32_16x16x32_bf16 v[112:115], v[170:173], v[178:181], v[112:115]
	v_mfma_f32_16x16x32_bf16 v[100:103], v[162:165], v[186:189], v[100:103]
	v_mfma_f32_16x16x32_bf16 v[96:99], v[170:173], v[186:189], v[96:99]
	v_mfma_f32_16x16x32_bf16 v[84:87], v[162:165], v[194:197], v[84:87]
	v_mfma_f32_16x16x32_bf16 v[80:83], v[170:173], v[194:197], v[80:83]
	v_mfma_f32_16x16x32_bf16 v[68:71], v[162:165], v[202:205], v[68:71]
	v_mfma_f32_16x16x32_bf16 v[64:67], v[170:173], v[202:205], v[64:67]
	s_barrier
	s_add_i32 s22, s80, s43
	s_add_i32 m0, s22, 0xffffff80
	ds_read_b128 v[174:177], v140 offset:49152
	ds_read_b128 v[178:181], v140 offset:50176
	ds_read_b128 v[182:185], v140 offset:51200
	ds_read_b128 v[186:189], v140 offset:52224
	ds_read_b128 v[190:193], v140 offset:53248
	ds_read_b128 v[194:197], v140 offset:54272
	ds_read_b128 v[198:201], v140 offset:55296
	ds_read_b128 v[202:205], v140 offset:56320
	global_load_lds_dwordx4 v208, vcc offset:128
	s_add_i32 m0, s22, 0x1f80
	s_add_u32 s22, vcc_lo, 0x80080
	s_addc_u32 s23, vcc_hi, 0
	s_add_i32 s80, s81, s43
	global_load_lds_dwordx4 v128, vcc offset:128
	s_mov_b32 m0, s80
	s_nop 0
	global_load_lds_dwordx4 v208, s[22:23]
	s_add_i32 m0, s80, 0x2000
	s_nop 0
	global_load_lds_dwordx4 v128, s[22:23]
	s_add_u32 s22, s92, s76
	s_addc_u32 s23, s93, s77
	s_cmp_eq_u32 s44, 0
	s_cselect_b32 s23, s15, s23
	s_cselect_b32 s22, s91, s22
	s_add_i32 m0, s9, 0xffffff80
	s_nop 0
	global_load_lds_dwordx4 v208, s[22:23] offset:128
	s_add_i32 m0, s12, 0xffffff80
	s_nop 0
	global_load_lds_dwordx4 v128, s[22:23] offset:128
	s_waitcnt vmcnt(8)
	s_waitcnt lgkmcnt(0)
	s_barrier
	v_mfma_f32_16x16x32_bf16 v[60:63], v[142:145], v[174:177], v[60:63]
	v_mfma_f32_16x16x32_bf16 v[56:59], v[150:153], v[174:177], v[56:59]
	v_mfma_f32_16x16x32_bf16 v[44:47], v[142:145], v[182:185], v[44:47]
	v_mfma_f32_16x16x32_bf16 v[40:43], v[150:153], v[182:185], v[40:43]
	v_mfma_f32_16x16x32_bf16 v[28:31], v[142:145], v[190:193], v[28:31]
	v_mfma_f32_16x16x32_bf16 v[24:27], v[150:153], v[190:193], v[24:27]
	v_mfma_f32_16x16x32_bf16 v[12:15], v[142:145], v[198:201], v[12:15]
	v_mfma_f32_16x16x32_bf16 v[8:11], v[150:153], v[198:201], v[8:11]
	v_mfma_f32_16x16x32_bf16 v[60:63], v[146:149], v[178:181], v[60:63]
	v_mfma_f32_16x16x32_bf16 v[56:59], v[154:157], v[178:181], v[56:59]
	v_mfma_f32_16x16x32_bf16 v[44:47], v[146:149], v[186:189], v[44:47]
	v_mfma_f32_16x16x32_bf16 v[40:43], v[154:157], v[186:189], v[40:43]
	v_mfma_f32_16x16x32_bf16 v[28:31], v[146:149], v[194:197], v[28:31]
	v_mfma_f32_16x16x32_bf16 v[24:27], v[154:157], v[194:197], v[24:27]
	v_mfma_f32_16x16x32_bf16 v[12:15], v[146:149], v[202:205], v[12:15]
	v_mfma_f32_16x16x32_bf16 v[8:11], v[154:157], v[202:205], v[8:11]
	v_mfma_f32_16x16x32_bf16 v[52:55], v[158:161], v[174:177], v[52:55]
	v_mfma_f32_16x16x32_bf16 v[48:51], v[166:169], v[174:177], v[48:51]
	v_mfma_f32_16x16x32_bf16 v[36:39], v[158:161], v[182:185], v[36:39]
	v_mfma_f32_16x16x32_bf16 v[32:35], v[166:169], v[182:185], v[32:35]
	v_mfma_f32_16x16x32_bf16 v[20:23], v[158:161], v[190:193], v[20:23]
	v_mfma_f32_16x16x32_bf16 v[16:19], v[166:169], v[190:193], v[16:19]
	v_mfma_f32_16x16x32_bf16 v[4:7], v[158:161], v[198:201], v[4:7]
	v_mfma_f32_16x16x32_bf16 v[0:3], v[166:169], v[198:201], v[0:3]
	v_mfma_f32_16x16x32_bf16 v[52:55], v[162:165], v[178:181], v[52:55]
	v_mfma_f32_16x16x32_bf16 v[48:51], v[170:173], v[178:181], v[48:51]
	v_mfma_f32_16x16x32_bf16 v[36:39], v[162:165], v[186:189], v[36:39]
	v_mfma_f32_16x16x32_bf16 v[32:35], v[170:173], v[186:189], v[32:35]
	v_mfma_f32_16x16x32_bf16 v[20:23], v[162:165], v[194:197], v[20:23]
	v_mfma_f32_16x16x32_bf16 v[16:19], v[170:173], v[194:197], v[16:19]
	v_mfma_f32_16x16x32_bf16 v[4:7], v[162:165], v[202:205], v[4:7]
	v_mfma_f32_16x16x32_bf16 v[0:3], v[170:173], v[202:205], v[0:3]
	s_barrier
	s_addk_i32 s44, 0x200
	s_add_u32 s76, s76, 0x100
	s_addc_u32 s77, s77, 0
	s_add_i32 s22, s82, 2
	v_lshl_add_u64 v[136:137], v[136:137], 0, s[58:59]
	s_cmp_gt_u32 s82, 29
	v_lshl_add_u64 v[134:135], v[134:135], 0, s[58:59]
	s_cbranch_scc1 .LBB0_1261
	s_mov_b32 s82, s22
	s_branch .LBB0_1257
